# nsa branch loop counted vmcnt only
# baseline (speedup 1.0000x reference)
.LBB0_123:
	s_ff1_i32_b32 s14, s12
	v_sub_co_u32_e64 v32, s[94:95], s12, 1
	s_lshl_b32 s15, s14, 6
	s_and_b64 s[78:79], s[94:95], exec
	s_cselect_b32 s15, 0, s15
	v_readfirstlane_b32 s13, v32
	v_add_u32_e32 v32, s15, v231
	v_ashrrev_i32_e32 v33, 31, v32
	s_waitcnt vmcnt(3)
	ds_write_b128 v236, v[80:83] offset:16384
	s_waitcnt vmcnt(2)
	ds_write2_b64 v237, v[84:85], v[86:87] offset1:1
	v_lshlrev_b64 v[32:33], 11, v[32:33]
	s_waitcnt lgkmcnt(0)
	s_barrier
	v_lshl_add_u64 v[32:33], v[152:153], 0, v[32:33]
	s_lshl_b32 s92, s15, 1
	global_load_dwordx4 v[80:83], v[32:33], off
	v_lshl_add_u64 v[32:33], v[154:155], 0, s[92:93]
	global_load_dwordx4 v[84:87], v[32:33], off
	s_lshl_b32 s15, 1, s10
	v_and_b32_e32 v32, s15, v235
	v_cmp_ne_u32_e32 vcc, 0, v32
	s_and_saveexec_b64 s[84:85], vcc
	s_cbranch_execz .LBB0_127
	ds_read_b128 v[244:247], v238 offset:16384
	v_and_b32_e32 v32, s15, v234
	v_cmp_ne_u32_e32 vcc, 0, v32
	s_cmp_lg_u32 s10, s89
	s_cselect_b64 s[78:79], -1, 0
	v_cndmask_b32_e64 v32, v208, -v232, vcc
	v_mov_b32_e32 v33, v32
	v_mov_b32_e32 v34, v32
	v_mov_b32_e32 v35, v32
	v_mov_b32_e32 v36, v32
	v_mov_b32_e32 v37, v32
	v_mov_b32_e32 v38, v32
	v_mov_b32_e32 v39, v32
	v_mov_b32_e32 v40, v32
	v_mov_b32_e32 v41, v32
	v_mov_b32_e32 v42, v32
	v_mov_b32_e32 v43, v32
	v_mov_b32_e32 v44, v32
	v_mov_b32_e32 v45, v32
	v_mov_b32_e32 v46, v32
	v_mov_b32_e32 v47, v32
	s_cmp_lg_u32 s10, s8
	s_cselect_b64 vcc, -1, 0
	s_waitcnt lgkmcnt(0)
	v_mfma_f32_32x32x16_bf16 v[48:63], v[244:247], v[64:67], v[32:47]
	ds_read_b128 v[244:247], v238 offset:20992
	s_and_b64 s[78:79], s[78:79], vcc
	s_and_b64 vcc, exec, s[78:79]
	s_waitcnt lgkmcnt(0)
	v_mfma_f32_32x32x16_bf16 v[32:47], v[244:247], v[64:67], v[32:47]
	ds_read_b128 v[244:247], v238 offset:16416
	s_waitcnt lgkmcnt(0)
	v_mfma_f32_32x32x16_bf16 v[48:63], v[244:247], v[68:71], v[48:63]
	ds_read_b128 v[244:247], v238 offset:21024
	s_waitcnt lgkmcnt(0)
	v_mfma_f32_32x32x16_bf16 v[32:47], v[244:247], v[68:71], v[32:47]
	ds_read_b128 v[244:247], v238 offset:16448
	s_waitcnt lgkmcnt(0)
	v_mfma_f32_32x32x16_bf16 v[48:63], v[244:247], v[72:75], v[48:63]
	ds_read_b128 v[244:247], v238 offset:21056
	s_waitcnt lgkmcnt(0)
	v_mfma_f32_32x32x16_bf16 v[32:47], v[244:247], v[72:75], v[32:47]
	ds_read_b128 v[244:247], v238 offset:16480
	s_waitcnt lgkmcnt(0)
	v_mfma_f32_32x32x16_bf16 v[48:63], v[244:247], v[76:79], v[48:63]
	ds_read_b128 v[244:247], v238 offset:21088
	s_waitcnt lgkmcnt(0)
	v_mfma_f32_32x32x16_bf16 v[32:47], v[244:247], v[76:79], v[32:47]
	s_cbranch_vccnz .LBB0_126
	v_lshl_or_b32 v156, s10, 6, v102
	v_cmp_lt_i32_e32 vcc, v156, v233
	v_cmp_gt_i32_e64 s[78:79], v156, v117
	s_or_b64 vcc, vcc, s[78:79]
	v_or_b32_e32 v157, 32, v156
	s_nop 2
	v_cndmask_b32_e32 v48, v48, v208, vcc
	v_cmp_lt_i32_e32 vcc, v157, v233
	v_cmp_gt_i32_e64 s[78:79], v157, v117
	s_or_b64 vcc, vcc, s[78:79]
	v_or_b32_e32 v157, 1, v156
	v_cndmask_b32_e32 v32, v32, v208, vcc
	v_cmp_lt_i32_e32 vcc, v157, v233
	v_cmp_ge_i32_e64 s[78:79], v156, v117
	s_or_b64 vcc, s[78:79], vcc
	v_or_b32_e32 v157, 33, v156
	v_cndmask_b32_e32 v49, v49, v208, vcc
	v_cmp_lt_i32_e32 vcc, v157, v233
	v_cmp_gt_i32_e64 s[78:79], v157, v117
	s_or_b64 vcc, vcc, s[78:79]
	v_or_b32_e32 v157, 2, v156
	v_cndmask_b32_e32 v33, v33, v208, vcc
	v_cmp_lt_i32_e32 vcc, v157, v233
	v_cmp_gt_i32_e64 s[78:79], v157, v117
	s_or_b64 vcc, vcc, s[78:79]
	v_or_b32_e32 v157, 34, v156
	v_cndmask_b32_e32 v50, v50, v208, vcc
	v_cmp_lt_i32_e32 vcc, v157, v233
	v_cmp_gt_i32_e64 s[78:79], v157, v117
	s_or_b64 vcc, vcc, s[78:79]
	v_or_b32_e32 v157, 3, v156
	v_cndmask_b32_e32 v34, v34, v208, vcc
	v_cmp_lt_i32_e32 vcc, v157, v233
	v_cmp_gt_i32_e64 s[78:79], v157, v117
	s_or_b64 vcc, vcc, s[78:79]
	v_or_b32_e32 v157, 35, v156
	v_cndmask_b32_e32 v51, v51, v208, vcc
	v_cmp_lt_i32_e32 vcc, v157, v233
	v_cmp_gt_i32_e64 s[78:79], v157, v117
	s_or_b64 vcc, vcc, s[78:79]
	v_or_b32_e32 v157, 8, v156
	v_cndmask_b32_e32 v35, v35, v208, vcc
	v_cmp_lt_i32_e32 vcc, v157, v233
	v_cmp_gt_i32_e64 s[78:79], v157, v117
	s_or_b64 vcc, vcc, s[78:79]
	v_or_b32_e32 v157, 40, v156
	v_cndmask_b32_e32 v52, v52, v208, vcc
	v_cmp_lt_i32_e32 vcc, v157, v233
	v_cmp_gt_i32_e64 s[78:79], v157, v117
	s_or_b64 vcc, vcc, s[78:79]
	v_or_b32_e32 v157, 9, v156
	v_cndmask_b32_e32 v36, v36, v208, vcc
	v_cmp_lt_i32_e32 vcc, v157, v233
	v_cmp_gt_i32_e64 s[78:79], v157, v117
	s_or_b64 vcc, vcc, s[78:79]
	v_or_b32_e32 v157, 41, v156
	v_cndmask_b32_e32 v53, v53, v208, vcc
	v_cmp_lt_i32_e32 vcc, v157, v233
	v_cmp_gt_i32_e64 s[78:79], v157, v117
	s_or_b64 vcc, vcc, s[78:79]
	v_or_b32_e32 v157, 10, v156
	v_cndmask_b32_e32 v37, v37, v208, vcc
	v_cmp_lt_i32_e32 vcc, v157, v233
	v_cmp_gt_i32_e64 s[78:79], v157, v117
	s_or_b64 vcc, vcc, s[78:79]
	v_or_b32_e32 v157, 42, v156
	v_cndmask_b32_e32 v54, v54, v208, vcc
	v_cmp_lt_i32_e32 vcc, v157, v233
	v_cmp_gt_i32_e64 s[78:79], v157, v117
	s_or_b64 vcc, vcc, s[78:79]
	v_or_b32_e32 v157, 11, v156
	v_cndmask_b32_e32 v38, v38, v208, vcc
	v_cmp_lt_i32_e32 vcc, v157, v233
	v_cmp_gt_i32_e64 s[78:79], v157, v117
	s_or_b64 vcc, vcc, s[78:79]
	v_or_b32_e32 v157, 43, v156
	v_cndmask_b32_e32 v55, v55, v208, vcc
	v_cmp_lt_i32_e32 vcc, v157, v233
	v_cmp_gt_i32_e64 s[78:79], v157, v117
	s_or_b64 vcc, vcc, s[78:79]
	v_or_b32_e32 v157, 16, v156
	v_cndmask_b32_e32 v39, v39, v208, vcc
	v_cmp_lt_i32_e32 vcc, v157, v233
	v_cmp_gt_i32_e64 s[78:79], v157, v117
	s_or_b64 vcc, vcc, s[78:79]
	v_or_b32_e32 v157, 48, v156
	v_cndmask_b32_e32 v56, v56, v208, vcc
	v_cmp_lt_i32_e32 vcc, v157, v233
	v_cmp_gt_i32_e64 s[78:79], v157, v117
	s_or_b64 vcc, vcc, s[78:79]
	v_or_b32_e32 v157, 17, v156
	v_cndmask_b32_e32 v40, v40, v208, vcc
	v_cmp_lt_i32_e32 vcc, v157, v233
	v_cmp_gt_i32_e64 s[78:79], v157, v117
	s_or_b64 vcc, vcc, s[78:79]
	v_or_b32_e32 v157, 49, v156
	v_cndmask_b32_e32 v57, v57, v208, vcc
	v_cmp_lt_i32_e32 vcc, v157, v233
	v_cmp_gt_i32_e64 s[78:79], v157, v117
	s_or_b64 vcc, vcc, s[78:79]
	v_or_b32_e32 v157, 18, v156
	v_cndmask_b32_e32 v41, v41, v208, vcc
	v_cmp_lt_i32_e32 vcc, v157, v233
	v_cmp_gt_i32_e64 s[78:79], v157, v117
	s_or_b64 vcc, vcc, s[78:79]
	v_or_b32_e32 v157, 50, v156
	v_cndmask_b32_e32 v58, v58, v208, vcc
	v_cmp_lt_i32_e32 vcc, v157, v233
	v_cmp_gt_i32_e64 s[78:79], v157, v117
	s_or_b64 vcc, vcc, s[78:79]
	v_or_b32_e32 v157, 19, v156
	v_cndmask_b32_e32 v42, v42, v208, vcc
	v_cmp_lt_i32_e32 vcc, v157, v233
	v_cmp_gt_i32_e64 s[78:79], v157, v117
	s_or_b64 vcc, vcc, s[78:79]
	v_or_b32_e32 v157, 51, v156
	v_cndmask_b32_e32 v59, v59, v208, vcc
	v_cmp_lt_i32_e32 vcc, v157, v233
	v_cmp_gt_i32_e64 s[78:79], v157, v117
	s_or_b64 vcc, vcc, s[78:79]
	v_or_b32_e32 v157, 24, v156
	v_cndmask_b32_e32 v43, v43, v208, vcc
	v_cmp_lt_i32_e32 vcc, v157, v233
	v_cmp_gt_i32_e64 s[78:79], v157, v117
	s_or_b64 vcc, vcc, s[78:79]
	v_or_b32_e32 v157, 56, v156
	v_cndmask_b32_e32 v60, v60, v208, vcc
	v_cmp_lt_i32_e32 vcc, v157, v233
	v_cmp_gt_i32_e64 s[78:79], v157, v117
	s_or_b64 vcc, vcc, s[78:79]
	v_or_b32_e32 v157, 25, v156
	v_cndmask_b32_e32 v44, v44, v208, vcc
	v_cmp_lt_i32_e32 vcc, v157, v233
	v_cmp_gt_i32_e64 s[78:79], v157, v117
	s_or_b64 vcc, vcc, s[78:79]
	v_or_b32_e32 v157, 57, v156
	v_cndmask_b32_e32 v61, v61, v208, vcc
	v_cmp_lt_i32_e32 vcc, v157, v233
	v_cmp_gt_i32_e64 s[78:79], v157, v117
	s_or_b64 vcc, vcc, s[78:79]
	v_or_b32_e32 v157, 26, v156
	v_cndmask_b32_e32 v45, v45, v208, vcc
	v_cmp_lt_i32_e32 vcc, v157, v233
	v_cmp_gt_i32_e64 s[78:79], v157, v117
	s_or_b64 vcc, vcc, s[78:79]
	v_or_b32_e32 v157, 58, v156
	v_cndmask_b32_e32 v62, v62, v208, vcc
	v_cmp_lt_i32_e32 vcc, v157, v233
	v_cmp_gt_i32_e64 s[78:79], v157, v117
	s_or_b64 vcc, vcc, s[78:79]
	v_or_b32_e32 v157, 27, v156
	v_cndmask_b32_e32 v46, v46, v208, vcc
	v_cmp_lt_i32_e32 vcc, v157, v233
	v_cmp_gt_i32_e64 s[78:79], v157, v117
	s_or_b64 vcc, vcc, s[78:79]
	v_or_b32_e32 v156, 59, v156
	v_cndmask_b32_e32 v63, v63, v208, vcc
	v_cmp_lt_i32_e32 vcc, v156, v233
	v_cmp_gt_i32_e64 s[78:79], v156, v117
	s_or_b64 vcc, vcc, s[78:79]
	v_cndmask_b32_e32 v47, v47, v208, vcc
